# scan loop head: post-barrier LDS reads issued in first-use order so the first wait covers two reads instead of seven
# speedup vs baseline: 1.0004x; 1.0004x over previous
.LBB0_1050:
	ds_read_b128 v[14:17], v0 offset:20480
	ds_read_b128 v[78:81], v89 offset:4096
	ds_read_b128 v[10:13], v0 offset:20496
	ds_read_b128 v[6:9], v0 offset:20512
	ds_read_b128 v[2:5], v0 offset:20528
	ds_read_b128 v[58:61], v89 offset:4352
	ds_read_b128 v[54:57], v89 offset:16384
	ds_read_b128 v[26:29], v89 offset:16640
	ds_read_b128 v[30:33], v89 offset:4608
	ds_read_b128 v[22:25], v90 offset:8704
	ds_read_b128 v[18:21], v89 offset:16896
	v_pk_mul_f32 v[66:67], v[74:75], v[108:109]
	s_waitcnt lgkmcnt(9)
	v_pk_mul_f32 v[78:79], v[14:15], v[78:79] op_sel_hi:[0,1]
	v_pk_fma_f32 v[66:67], v[76:77], v[110:111], v[66:67]
	v_pk_mul_f32 v[80:81], v[14:15], v[80:81] op_sel_hi:[0,1]
	v_add_f32_e32 v66, v66, v67
	v_pk_fma_f32 v[62:63], v[74:75], v[100:101], v[78:79]
	v_pk_fma_f32 v[64:65], v[76:77], v[102:103], v[80:81]
	v_add_f32_dpp v66, v66, v66 quad_perm:[1,0,3,2] row_mask:0xf bank_mask:0xf bound_ctrl:1
	v_mov_b32_e32 v0, v17
	s_waitcnt lgkmcnt(8)
	v_mov_b32_e32 v82, v13
	v_add_f32_dpp v66, v66, v66 quad_perm:[2,3,0,1] row_mask:0xf bank_mask:0xf bound_ctrl:1
	s_waitcnt lgkmcnt(7)
	v_mov_b32_e32 v84, v9
	s_waitcnt lgkmcnt(6)
	v_mov_b32_e32 v86, v5
	v_add_f32_dpp v66, v66, v66 row_half_mirror row_mask:0xf bank_mask:0xf bound_ctrl:1
	s_add_i32 s26, s26, 1
	s_nop 0
	v_add_f32_dpp v66, v66, v66 row_ror:8 row_mask:0xf bank_mask:0xf bound_ctrl:1
	v_pk_fma_f32 v[62:63], v[120:121], v[66:67], v[62:63] op_sel_hi:[1,0,1] neg_lo:[1,0,0] neg_hi:[1,0,0]
	v_pk_fma_f32 v[64:65], v[122:123], v[66:67], v[64:65] op_sel_hi:[1,0,1] neg_lo:[1,0,0] neg_hi:[1,0,0]
	v_pk_mul_f32 v[50:51], v[112:113], v[62:63]
	v_pk_mul_f32 v[46:47], v[104:105], v[62:63]
	v_pk_fma_f32 v[50:51], v[114:115], v[64:65], v[50:51]
	s_waitcnt lgkmcnt(5)
	v_pk_fma_f32 v[66:67], v[14:15], v[58:59], v[46:47] op_sel:[1,0,0]
	v_add_f32_e32 v47, v50, v51
	v_pk_mul_f32 v[48:49], v[106:107], v[64:65]
	s_waitcnt lgkmcnt(4)
	v_pk_mul_f32 v[56:57], v[56:57], v[64:65]
	v_add_f32_dpp v68, v47, v47 quad_perm:[1,0,3,2] row_mask:0xf bank_mask:0xf bound_ctrl:1
	v_pk_fma_f32 v[14:15], v[14:15], v[60:61], v[48:49] op_sel:[1,0,0]
	v_pk_fma_f32 v[54:55], v[54:55], v[62:63], v[56:57]
	v_add_f32_dpp v68, v68, v68 quad_perm:[2,3,0,1] row_mask:0xf bank_mask:0xf bound_ctrl:1
	v_add_f32_e32 v92, v54, v55
	s_nop 0
	v_add_f32_dpp v68, v68, v68 row_half_mirror row_mask:0xf bank_mask:0xf bound_ctrl:1
	ds_read_b128 v[46:49], v90 offset:768
	ds_read_b128 v[50:53], v89 offset:4864
	ds_read_b128 v[54:57], v90 offset:4864
	ds_read_b128 v[58:61], v90 offset:8960
	ds_read_b128 v[62:65], v89 offset:17152
	v_add_f32_dpp v68, v68, v68 row_ror:8 row_mask:0xf bank_mask:0xf bound_ctrl:1
	v_pk_fma_f32 v[42:43], v[128:129], v[68:69], v[66:67] op_sel_hi:[1,0,1] neg_lo:[1,0,0] neg_hi:[1,0,0]
	v_pk_fma_f32 v[14:15], v[130:131], v[68:69], v[14:15] op_sel_hi:[1,0,1] neg_lo:[1,0,0] neg_hi:[1,0,0]
	v_pk_mul_f32 v[38:39], v[124:125], v[42:43]
	s_waitcnt lgkmcnt(8)
	v_pk_mul_f32 v[28:29], v[28:29], v[14:15]
	v_pk_mul_f32 v[36:37], v[118:119], v[14:15]
	v_pk_fma_f32 v[14:15], v[126:127], v[14:15], v[38:39]
	v_pk_mul_f32 v[34:35], v[116:117], v[42:43]
	v_add_f32_e32 v14, v14, v15
	v_pk_fma_f32 v[26:27], v[26:27], v[42:43], v[28:29]
	s_waitcnt lgkmcnt(7)
	v_pk_fma_f32 v[42:43], v[16:17], v[30:31], v[34:35] op_sel_hi:[0,1,1]
	v_add_f32_dpp v66, v14, v14 quad_perm:[1,0,3,2] row_mask:0xf bank_mask:0xf bound_ctrl:1
	v_pk_fma_f32 v[44:45], v[16:17], v[32:33], v[36:37] op_sel_hi:[0,1,1]
	v_add_f32_e32 v93, v26, v27
	v_add_f32_dpp v66, v66, v66 quad_perm:[2,3,0,1] row_mask:0xf bank_mask:0xf bound_ctrl:1
	ds_read_b128 v[14:17], v90 offset:1024
	ds_read_b128 v[26:29], v89 offset:5120
	ds_read_b128 v[30:33], v90 offset:5120
	ds_read_b128 v[34:37], v90 offset:9216
	ds_read_b128 v[38:41], v89 offset:17408
	v_add_f32_dpp v66, v66, v66 row_half_mirror row_mask:0xf bank_mask:0xf bound_ctrl:1
	s_nop 1
	v_add_f32_dpp v66, v66, v66 row_ror:8 row_mask:0xf bank_mask:0xf bound_ctrl:1
	s_waitcnt lgkmcnt(11)
	v_pk_fma_f32 v[22:23], v[22:23], v[66:67], v[42:43] op_sel_hi:[1,0,1] neg_lo:[1,0,0] neg_hi:[1,0,0]
	v_pk_fma_f32 v[24:25], v[24:25], v[66:67], v[44:45] op_sel_hi:[1,0,1] neg_lo:[1,0,0] neg_hi:[1,0,0]
	s_waitcnt lgkmcnt(7)
	v_pk_mul_f32 v[42:43], v[54:55], v[22:23]
	v_pk_mul_f32 v[20:21], v[20:21], v[24:25]
	v_pk_mul_f32 v[44:45], v[46:47], v[22:23]
	v_pk_mul_f32 v[46:47], v[48:49], v[24:25]
	v_pk_fma_f32 v[18:19], v[18:19], v[22:23], v[20:21]
	v_pk_fma_f32 v[20:21], v[56:57], v[24:25], v[42:43]
	v_pk_fma_f32 v[54:55], v[0:1], v[50:51], v[44:45] op_sel_hi:[0,1,1]
	v_pk_fma_f32 v[56:57], v[0:1], v[52:53], v[46:47] op_sel_hi:[0,1,1]
	v_add_f32_e32 v94, v18, v19
	v_add_f32_e32 v18, v20, v21
	s_nop 0
	s_nop 0
	v_add_f32_dpp v0, v18, v18 quad_perm:[1,0,3,2] row_mask:0xf bank_mask:0xf bound_ctrl:1
	ds_read_b128 v[18:21], v90 offset:1280
	ds_read_b128 v[22:25], v89 offset:5376
	v_add_f32_dpp v0, v0, v0 quad_perm:[2,3,0,1] row_mask:0xf bank_mask:0xf bound_ctrl:1
	ds_read_b128 v[42:45], v90 offset:5376
	ds_read_b128 v[46:49], v90 offset:9472
	v_add_f32_dpp v0, v0, v0 row_half_mirror row_mask:0xf bank_mask:0xf bound_ctrl:1
	ds_read_b128 v[50:53], v89 offset:17664
	s_nop 0
	v_add_f32_dpp v0, v0, v0 row_ror:8 row_mask:0xf bank_mask:0xf bound_ctrl:1
	s_waitcnt lgkmcnt(11)
	v_pk_fma_f32 v[54:55], v[58:59], v[0:1], v[54:55] op_sel_hi:[1,0,1] neg_lo:[1,0,0] neg_hi:[1,0,0]
	v_pk_fma_f32 v[56:57], v[60:61], v[0:1], v[56:57] op_sel_hi:[1,0,1] neg_lo:[1,0,0] neg_hi:[1,0,0]
	s_waitcnt lgkmcnt(7)
	v_pk_mul_f32 v[30:31], v[30:31], v[54:55]
	v_pk_mul_f32 v[58:59], v[64:65], v[56:57]
	v_pk_mul_f32 v[14:15], v[14:15], v[54:55]
	v_pk_fma_f32 v[54:55], v[62:63], v[54:55], v[58:59]
	v_pk_fma_f32 v[30:31], v[32:33], v[56:57], v[30:31]
	v_pk_fma_f32 v[62:63], v[10:11], v[26:27], v[14:15] op_sel_hi:[0,1,1]
	v_add_f32_e32 v95, v54, v55
	v_add_f32_e32 v14, v30, v31
	ds_write_b128 v91, v[92:95] offset:43008
	v_pk_mul_f32 v[16:17], v[16:17], v[56:57]
	v_add_f32_dpp v0, v14, v14 quad_perm:[1,0,3,2] row_mask:0xf bank_mask:0xf bound_ctrl:1
	v_pk_fma_f32 v[64:65], v[10:11], v[28:29], v[16:17] op_sel_hi:[0,1,1]
	ds_read_b128 v[14:17], v90 offset:1536
	v_add_f32_dpp v0, v0, v0 quad_perm:[2,3,0,1] row_mask:0xf bank_mask:0xf bound_ctrl:1
	ds_read_b128 v[26:29], v89 offset:5632
	ds_read_b128 v[30:33], v90 offset:5632
	v_add_f32_dpp v0, v0, v0 row_half_mirror row_mask:0xf bank_mask:0xf bound_ctrl:1
	ds_read_b128 v[54:57], v90 offset:9728
	ds_read_b128 v[58:61], v89 offset:17920
	v_add_f32_dpp v0, v0, v0 row_ror:8 row_mask:0xf bank_mask:0xf bound_ctrl:1
	s_waitcnt lgkmcnt(12)
	v_pk_fma_f32 v[34:35], v[34:35], v[0:1], v[62:63] op_sel_hi:[1,0,1] neg_lo:[1,0,0] neg_hi:[1,0,0]
	v_pk_fma_f32 v[36:37], v[36:37], v[0:1], v[64:65] op_sel_hi:[1,0,1] neg_lo:[1,0,0] neg_hi:[1,0,0]
	s_waitcnt lgkmcnt(8)
	v_pk_mul_f32 v[42:43], v[42:43], v[34:35]
	v_pk_mul_f32 v[40:41], v[40:41], v[36:37]
	v_pk_mul_f32 v[18:19], v[18:19], v[34:35]
	v_pk_mul_f32 v[20:21], v[20:21], v[36:37]
	v_pk_fma_f32 v[34:35], v[38:39], v[34:35], v[40:41]
	v_pk_fma_f32 v[36:37], v[44:45], v[36:37], v[42:43]
	v_pk_fma_f32 v[62:63], v[10:11], v[22:23], v[18:19] op_sel:[1,0,0]
	v_add_f32_e32 v18, v36, v37
	v_add_f32_e32 v96, v34, v35
	v_pk_fma_f32 v[10:11], v[10:11], v[24:25], v[20:21] op_sel:[1,0,0]
	v_add_f32_dpp v0, v18, v18 quad_perm:[1,0,3,2] row_mask:0xf bank_mask:0xf bound_ctrl:1
	ds_read_b128 v[18:21], v90 offset:1792
	ds_read_b128 v[22:25], v89 offset:5888
	v_add_f32_dpp v0, v0, v0 quad_perm:[2,3,0,1] row_mask:0xf bank_mask:0xf bound_ctrl:1
	ds_read_b128 v[34:37], v90 offset:5888
	ds_read_b128 v[38:41], v90 offset:9984
	v_add_f32_dpp v0, v0, v0 row_half_mirror row_mask:0xf bank_mask:0xf bound_ctrl:1
	ds_read_b128 v[42:45], v89 offset:18176
	s_nop 0
	v_add_f32_dpp v0, v0, v0 row_ror:8 row_mask:0xf bank_mask:0xf bound_ctrl:1
	s_waitcnt lgkmcnt(12)
	v_pk_fma_f32 v[46:47], v[46:47], v[0:1], v[62:63] op_sel_hi:[1,0,1] neg_lo:[1,0,0] neg_hi:[1,0,0]
	v_pk_fma_f32 v[10:11], v[48:49], v[0:1], v[10:11] op_sel_hi:[1,0,1] neg_lo:[1,0,0] neg_hi:[1,0,0]
	s_waitcnt lgkmcnt(7)
	v_pk_mul_f32 v[30:31], v[30:31], v[46:47]
	v_pk_mul_f32 v[48:49], v[52:53], v[10:11]
	v_pk_mul_f32 v[14:15], v[14:15], v[46:47]
	v_pk_mul_f32 v[16:17], v[16:17], v[10:11]
	v_pk_fma_f32 v[46:47], v[50:51], v[46:47], v[48:49]
	v_pk_fma_f32 v[10:11], v[32:33], v[10:11], v[30:31]
	v_add_f32_e32 v10, v10, v11
	v_add_f32_e32 v97, v46, v47
	v_pk_fma_f32 v[50:51], v[12:13], v[26:27], v[14:15] op_sel_hi:[0,1,1]
	v_add_f32_dpp v0, v10, v10 quad_perm:[1,0,3,2] row_mask:0xf bank_mask:0xf bound_ctrl:1
	v_pk_fma_f32 v[52:53], v[12:13], v[28:29], v[16:17] op_sel_hi:[0,1,1]
	ds_read_b128 v[10:13], v90 offset:2048
	v_add_f32_dpp v0, v0, v0 quad_perm:[2,3,0,1] row_mask:0xf bank_mask:0xf bound_ctrl:1
	ds_read_b128 v[14:17], v89 offset:6144
	ds_read_b128 v[26:29], v90 offset:6144
	v_add_f32_dpp v0, v0, v0 row_half_mirror row_mask:0xf bank_mask:0xf bound_ctrl:1
	ds_read_b128 v[30:33], v90 offset:10240
	ds_read_b128 v[46:49], v89 offset:18432
	v_add_f32_dpp v0, v0, v0 row_ror:8 row_mask:0xf bank_mask:0xf bound_ctrl:1
	s_waitcnt lgkmcnt(11)
	v_pk_fma_f32 v[50:51], v[54:55], v[0:1], v[50:51] op_sel_hi:[1,0,1] neg_lo:[1,0,0] neg_hi:[1,0,0]
	v_pk_fma_f32 v[52:53], v[56:57], v[0:1], v[52:53] op_sel_hi:[1,0,1] neg_lo:[1,0,0] neg_hi:[1,0,0]
	s_waitcnt lgkmcnt(7)
	v_pk_mul_f32 v[34:35], v[34:35], v[50:51]
	v_pk_mul_f32 v[54:55], v[60:61], v[52:53]
	v_pk_mul_f32 v[18:19], v[18:19], v[50:51]
	v_pk_fma_f32 v[50:51], v[58:59], v[50:51], v[54:55]
	v_pk_fma_f32 v[34:35], v[36:37], v[52:53], v[34:35]
	v_pk_fma_f32 v[58:59], v[82:83], v[22:23], v[18:19] op_sel_hi:[0,1,1]
	v_add_f32_e32 v18, v34, v35
	v_add_f32_e32 v98, v50, v51
	v_pk_mul_f32 v[20:21], v[20:21], v[52:53]
	v_add_f32_dpp v0, v18, v18 quad_perm:[1,0,3,2] row_mask:0xf bank_mask:0xf bound_ctrl:1
	v_pk_fma_f32 v[60:61], v[82:83], v[24:25], v[20:21] op_sel_hi:[0,1,1]
	ds_read_b128 v[18:21], v90 offset:2304
	v_add_f32_dpp v0, v0, v0 quad_perm:[2,3,0,1] row_mask:0xf bank_mask:0xf bound_ctrl:1
	ds_read_b128 v[22:25], v89 offset:6400
	ds_read_b128 v[34:37], v90 offset:6400
	v_add_f32_dpp v0, v0, v0 row_half_mirror row_mask:0xf bank_mask:0xf bound_ctrl:1
	ds_read_b128 v[50:53], v90 offset:10496
	ds_read_b128 v[54:57], v89 offset:18688
	v_add_f32_dpp v0, v0, v0 row_ror:8 row_mask:0xf bank_mask:0xf bound_ctrl:1
	s_waitcnt lgkmcnt(11)
	v_pk_fma_f32 v[38:39], v[38:39], v[0:1], v[58:59] op_sel_hi:[1,0,1] neg_lo:[1,0,0] neg_hi:[1,0,0]
	v_pk_fma_f32 v[40:41], v[40:41], v[0:1], v[60:61] op_sel_hi:[1,0,1] neg_lo:[1,0,0] neg_hi:[1,0,0]
	s_waitcnt lgkmcnt(7)
	v_pk_mul_f32 v[26:27], v[26:27], v[38:39]
	v_pk_mul_f32 v[44:45], v[44:45], v[40:41]
	v_pk_mul_f32 v[10:11], v[10:11], v[38:39]
	v_pk_fma_f32 v[38:39], v[42:43], v[38:39], v[44:45]
	v_pk_fma_f32 v[26:27], v[28:29], v[40:41], v[26:27]
	v_pk_fma_f32 v[58:59], v[6:7], v[14:15], v[10:11] op_sel_hi:[0,1,1]
	v_add_f32_e32 v99, v38, v39
	v_add_f32_e32 v10, v26, v27
	ds_write_b128 v91, v[96:99] offset:47104
	v_pk_mul_f32 v[12:13], v[12:13], v[40:41]
	v_add_f32_dpp v0, v10, v10 quad_perm:[1,0,3,2] row_mask:0xf bank_mask:0xf bound_ctrl:1
	v_pk_fma_f32 v[60:61], v[6:7], v[16:17], v[12:13] op_sel_hi:[0,1,1]
	ds_read_b128 v[10:13], v90 offset:2560
	v_add_f32_dpp v0, v0, v0 quad_perm:[2,3,0,1] row_mask:0xf bank_mask:0xf bound_ctrl:1
	ds_read_b128 v[14:17], v89 offset:6656
	ds_read_b128 v[26:29], v90 offset:6656
	v_add_f32_dpp v0, v0, v0 row_half_mirror row_mask:0xf bank_mask:0xf bound_ctrl:1
	ds_read_b128 v[38:41], v90 offset:10752
	ds_read_b128 v[42:45], v89 offset:18944
	v_add_f32_dpp v0, v0, v0 row_ror:8 row_mask:0xf bank_mask:0xf bound_ctrl:1
	s_waitcnt lgkmcnt(12)
	v_pk_fma_f32 v[30:31], v[30:31], v[0:1], v[58:59] op_sel_hi:[1,0,1] neg_lo:[1,0,0] neg_hi:[1,0,0]
	v_pk_fma_f32 v[32:33], v[32:33], v[0:1], v[60:61] op_sel_hi:[1,0,1] neg_lo:[1,0,0] neg_hi:[1,0,0]
	s_waitcnt lgkmcnt(8)
	v_pk_mul_f32 v[34:35], v[34:35], v[30:31]
	v_pk_mul_f32 v[48:49], v[48:49], v[32:33]
	v_pk_mul_f32 v[18:19], v[18:19], v[30:31]
	v_pk_mul_f32 v[20:21], v[20:21], v[32:33]
	v_pk_fma_f32 v[30:31], v[46:47], v[30:31], v[48:49]
	v_pk_fma_f32 v[32:33], v[36:37], v[32:33], v[34:35]
	v_pk_fma_f32 v[58:59], v[6:7], v[22:23], v[18:19] op_sel:[1,0,0]
	v_add_f32_e32 v18, v32, v33
	v_add_f32_e32 v92, v30, v31
	v_pk_fma_f32 v[6:7], v[6:7], v[24:25], v[20:21] op_sel:[1,0,0]
	v_add_f32_dpp v0, v18, v18 quad_perm:[1,0,3,2] row_mask:0xf bank_mask:0xf bound_ctrl:1
	ds_read_b128 v[18:21], v90 offset:2816
	ds_read_b128 v[22:25], v89 offset:6912
	v_add_f32_dpp v0, v0, v0 quad_perm:[2,3,0,1] row_mask:0xf bank_mask:0xf bound_ctrl:1
	ds_read_b128 v[30:33], v90 offset:6912
	ds_read_b128 v[34:37], v90 offset:11008
	v_add_f32_dpp v0, v0, v0 row_half_mirror row_mask:0xf bank_mask:0xf bound_ctrl:1
	ds_read_b128 v[46:49], v89 offset:19200
	s_nop 0
	v_add_f32_dpp v0, v0, v0 row_ror:8 row_mask:0xf bank_mask:0xf bound_ctrl:1
	s_waitcnt lgkmcnt(12)
	v_pk_fma_f32 v[50:51], v[50:51], v[0:1], v[58:59] op_sel_hi:[1,0,1] neg_lo:[1,0,0] neg_hi:[1,0,0]
	v_pk_fma_f32 v[6:7], v[52:53], v[0:1], v[6:7] op_sel_hi:[1,0,1] neg_lo:[1,0,0] neg_hi:[1,0,0]
	s_waitcnt lgkmcnt(7)
	v_pk_mul_f32 v[26:27], v[26:27], v[50:51]
	v_pk_mul_f32 v[52:53], v[56:57], v[6:7]
	v_pk_mul_f32 v[10:11], v[10:11], v[50:51]
	v_pk_mul_f32 v[12:13], v[12:13], v[6:7]
	v_pk_fma_f32 v[50:51], v[54:55], v[50:51], v[52:53]
	v_pk_fma_f32 v[6:7], v[28:29], v[6:7], v[26:27]
	v_add_f32_e32 v6, v6, v7
	v_add_f32_e32 v93, v50, v51
	v_pk_fma_f32 v[54:55], v[8:9], v[14:15], v[10:11] op_sel_hi:[0,1,1]
	v_add_f32_dpp v0, v6, v6 quad_perm:[1,0,3,2] row_mask:0xf bank_mask:0xf bound_ctrl:1
	v_pk_fma_f32 v[56:57], v[8:9], v[16:17], v[12:13] op_sel_hi:[0,1,1]
	ds_read_b128 v[6:9], v90 offset:3072
	v_add_f32_dpp v0, v0, v0 quad_perm:[2,3,0,1] row_mask:0xf bank_mask:0xf bound_ctrl:1
	ds_read_b128 v[10:13], v89 offset:7168
	ds_read_b128 v[14:17], v90 offset:7168
	v_add_f32_dpp v0, v0, v0 row_half_mirror row_mask:0xf bank_mask:0xf bound_ctrl:1
	ds_read_b128 v[26:29], v90 offset:11264
	ds_read_b128 v[50:53], v89 offset:19456
	v_add_f32_dpp v0, v0, v0 row_ror:8 row_mask:0xf bank_mask:0xf bound_ctrl:1
	s_waitcnt lgkmcnt(11)
	v_pk_fma_f32 v[38:39], v[38:39], v[0:1], v[54:55] op_sel_hi:[1,0,1] neg_lo:[1,0,0] neg_hi:[1,0,0]
	v_pk_fma_f32 v[40:41], v[40:41], v[0:1], v[56:57] op_sel_hi:[1,0,1] neg_lo:[1,0,0] neg_hi:[1,0,0]
	s_waitcnt lgkmcnt(7)
	v_pk_mul_f32 v[30:31], v[30:31], v[38:39]
	v_pk_mul_f32 v[44:45], v[44:45], v[40:41]
	v_pk_mul_f32 v[18:19], v[18:19], v[38:39]
	v_pk_fma_f32 v[38:39], v[42:43], v[38:39], v[44:45]
	v_pk_fma_f32 v[30:31], v[32:33], v[40:41], v[30:31]
	v_pk_fma_f32 v[54:55], v[84:85], v[22:23], v[18:19] op_sel_hi:[0,1,1]
	v_add_f32_e32 v18, v30, v31
	v_add_f32_e32 v94, v38, v39
	v_pk_mul_f32 v[20:21], v[20:21], v[40:41]
	v_add_f32_dpp v0, v18, v18 quad_perm:[1,0,3,2] row_mask:0xf bank_mask:0xf bound_ctrl:1
	v_pk_fma_f32 v[56:57], v[84:85], v[24:25], v[20:21] op_sel_hi:[0,1,1]
	ds_read_b128 v[18:21], v90 offset:3328
	v_add_f32_dpp v0, v0, v0 quad_perm:[2,3,0,1] row_mask:0xf bank_mask:0xf bound_ctrl:1
	ds_read_b128 v[22:25], v89 offset:7424
	ds_read_b128 v[30:33], v90 offset:7424
	v_add_f32_dpp v0, v0, v0 row_half_mirror row_mask:0xf bank_mask:0xf bound_ctrl:1
	ds_read_b128 v[38:41], v90 offset:11520
	ds_read_b128 v[42:45], v89 offset:19712
	v_add_f32_dpp v0, v0, v0 row_ror:8 row_mask:0xf bank_mask:0xf bound_ctrl:1
	s_waitcnt lgkmcnt(11)
	v_pk_fma_f32 v[34:35], v[34:35], v[0:1], v[54:55] op_sel_hi:[1,0,1] neg_lo:[1,0,0] neg_hi:[1,0,0]
	v_pk_fma_f32 v[36:37], v[36:37], v[0:1], v[56:57] op_sel_hi:[1,0,1] neg_lo:[1,0,0] neg_hi:[1,0,0]
	s_waitcnt lgkmcnt(7)
	v_pk_mul_f32 v[14:15], v[14:15], v[34:35]
	v_pk_mul_f32 v[48:49], v[48:49], v[36:37]
	v_pk_mul_f32 v[6:7], v[6:7], v[34:35]
	v_pk_fma_f32 v[34:35], v[46:47], v[34:35], v[48:49]
	v_pk_fma_f32 v[14:15], v[16:17], v[36:37], v[14:15]
	v_pk_fma_f32 v[54:55], v[2:3], v[10:11], v[6:7] op_sel_hi:[0,1,1]
	v_add_f32_e32 v95, v34, v35
	v_add_f32_e32 v6, v14, v15
	ds_write_b128 v91, v[92:95] offset:51200
	v_pk_mul_f32 v[8:9], v[8:9], v[36:37]
	v_add_f32_dpp v0, v6, v6 quad_perm:[1,0,3,2] row_mask:0xf bank_mask:0xf bound_ctrl:1
	v_pk_fma_f32 v[56:57], v[2:3], v[12:13], v[8:9] op_sel_hi:[0,1,1]
	ds_read_b128 v[6:9], v90 offset:3584
	v_add_f32_dpp v0, v0, v0 quad_perm:[2,3,0,1] row_mask:0xf bank_mask:0xf bound_ctrl:1
	ds_read_b128 v[10:13], v89 offset:7680
	ds_read_b128 v[14:17], v90 offset:7680
	v_add_f32_dpp v0, v0, v0 row_half_mirror row_mask:0xf bank_mask:0xf bound_ctrl:1
	ds_read_b128 v[34:37], v90 offset:11776
	ds_read_b128 v[46:49], v89 offset:19968
	v_add_f32_dpp v0, v0, v0 row_ror:8 row_mask:0xf bank_mask:0xf bound_ctrl:1
	s_waitcnt lgkmcnt(12)
	v_pk_fma_f32 v[26:27], v[26:27], v[0:1], v[54:55] op_sel_hi:[1,0,1] neg_lo:[1,0,0] neg_hi:[1,0,0]
	v_pk_fma_f32 v[28:29], v[28:29], v[0:1], v[56:57] op_sel_hi:[1,0,1] neg_lo:[1,0,0] neg_hi:[1,0,0]
	s_waitcnt lgkmcnt(8)
	v_pk_mul_f32 v[30:31], v[30:31], v[26:27]
	v_pk_mul_f32 v[52:53], v[52:53], v[28:29]
	v_pk_mul_f32 v[18:19], v[18:19], v[26:27]
	v_pk_mul_f32 v[20:21], v[20:21], v[28:29]
	v_pk_fma_f32 v[26:27], v[50:51], v[26:27], v[52:53]
	v_pk_fma_f32 v[28:29], v[32:33], v[28:29], v[30:31]
	v_pk_fma_f32 v[54:55], v[2:3], v[22:23], v[18:19] op_sel:[1,0,0]
	v_add_f32_e32 v18, v28, v29
	v_add_f32_e32 v96, v26, v27
	v_pk_fma_f32 v[2:3], v[2:3], v[24:25], v[20:21] op_sel:[1,0,0]
	v_add_f32_dpp v0, v18, v18 quad_perm:[1,0,3,2] row_mask:0xf bank_mask:0xf bound_ctrl:1
	ds_read_b128 v[18:21], v90 offset:3840
	ds_read_b128 v[22:25], v89 offset:7936
	v_add_f32_dpp v0, v0, v0 quad_perm:[2,3,0,1] row_mask:0xf bank_mask:0xf bound_ctrl:1
	ds_read_b128 v[26:29], v90 offset:7936
	ds_read_b128 v[30:33], v90 offset:12032
	v_add_f32_dpp v0, v0, v0 row_half_mirror row_mask:0xf bank_mask:0xf bound_ctrl:1
	ds_read_b128 v[50:53], v89 offset:20224
	s_nop 0
	v_add_f32_dpp v0, v0, v0 row_ror:8 row_mask:0xf bank_mask:0xf bound_ctrl:1
	s_waitcnt lgkmcnt(12)
	v_pk_fma_f32 v[38:39], v[38:39], v[0:1], v[54:55] op_sel_hi:[1,0,1] neg_lo:[1,0,0] neg_hi:[1,0,0]
	v_pk_fma_f32 v[2:3], v[40:41], v[0:1], v[2:3] op_sel_hi:[1,0,1] neg_lo:[1,0,0] neg_hi:[1,0,0]
	s_waitcnt lgkmcnt(7)
	v_pk_mul_f32 v[14:15], v[14:15], v[38:39]
	v_pk_mul_f32 v[40:41], v[44:45], v[2:3]
	v_pk_mul_f32 v[8:9], v[8:9], v[2:3]
	v_pk_fma_f32 v[2:3], v[16:17], v[2:3], v[14:15]
	v_pk_mul_f32 v[6:7], v[6:7], v[38:39]
	v_add_f32_e32 v0, v2, v3
	v_pk_fma_f32 v[6:7], v[4:5], v[10:11], v[6:7] op_sel_hi:[0,1,1]
	v_pk_fma_f32 v[4:5], v[4:5], v[12:13], v[8:9] op_sel_hi:[0,1,1]
	v_add_f32_dpp v0, v0, v0 quad_perm:[1,0,3,2] row_mask:0xf bank_mask:0xf bound_ctrl:1
	v_pk_fma_f32 v[38:39], v[42:43], v[38:39], v[40:41]
	ds_read_b128 v[108:111], v88 offset:4096
	v_add_f32_dpp v0, v0, v0 quad_perm:[2,3,0,1] row_mask:0xf bank_mask:0xf bound_ctrl:1
	v_add_f32_e32 v97, v38, v39
	ds_read_b128 v[100:103], v88
	v_add_f32_dpp v0, v0, v0 row_half_mirror row_mask:0xf bank_mask:0xf bound_ctrl:1
	ds_read_b128 v[120:123], v88 offset:8192
	ds_read_b128 v[112:115], v88 offset:4352
	v_add_f32_dpp v0, v0, v0 row_ror:8 row_mask:0xf bank_mask:0xf bound_ctrl:1
	s_waitcnt lgkmcnt(10)
	v_pk_fma_f32 v[2:3], v[34:35], v[0:1], v[6:7] op_sel_hi:[1,0,1] neg_lo:[1,0,0] neg_hi:[1,0,0]
	v_pk_fma_f32 v[4:5], v[36:37], v[0:1], v[4:5] op_sel_hi:[1,0,1] neg_lo:[1,0,0] neg_hi:[1,0,0]
	s_waitcnt lgkmcnt(6)
	v_pk_mul_f32 v[8:9], v[26:27], v[2:3]
	v_pk_mul_f32 v[6:7], v[48:49], v[4:5]
	v_pk_mul_f32 v[10:11], v[18:19], v[2:3]
	v_pk_mul_f32 v[12:13], v[20:21], v[4:5]
	v_pk_fma_f32 v[2:3], v[46:47], v[2:3], v[6:7]
	v_pk_fma_f32 v[4:5], v[28:29], v[4:5], v[8:9]
	v_add_f32_e32 v98, v2, v3
	v_add_f32_e32 v2, v4, v5
	v_pk_fma_f32 v[8:9], v[86:87], v[24:25], v[12:13] op_sel_hi:[0,1,1]
	s_nop 0
	v_add_f32_dpp v0, v2, v2 quad_perm:[1,0,3,2] row_mask:0xf bank_mask:0xf bound_ctrl:1
	v_pk_fma_f32 v[6:7], v[86:87], v[22:23], v[10:11] op_sel_hi:[0,1,1]
	ds_read_b128 v[104:107], v88 offset:256
	v_add_f32_dpp v0, v0, v0 quad_perm:[2,3,0,1] row_mask:0xf bank_mask:0xf bound_ctrl:1
	ds_read_b128 v[128:131], v88 offset:8448
	ds_read_b128 v[124:127], v88 offset:4608
	v_add_f32_dpp v0, v0, v0 row_half_mirror row_mask:0xf bank_mask:0xf bound_ctrl:1
	ds_read_b128 v[116:119], v88 offset:512
	s_nop 0
	v_add_f32_dpp v0, v0, v0 row_ror:8 row_mask:0xf bank_mask:0xf bound_ctrl:1
	s_waitcnt lgkmcnt(9)
	v_pk_fma_f32 v[76:77], v[32:33], v[0:1], v[8:9] op_sel_hi:[1,0,1] neg_lo:[1,0,0] neg_hi:[1,0,0]
	v_pk_fma_f32 v[74:75], v[30:31], v[0:1], v[6:7] op_sel_hi:[1,0,1] neg_lo:[1,0,0] neg_hi:[1,0,0]
	s_waitcnt lgkmcnt(8)
	v_pk_mul_f32 v[2:3], v[52:53], v[76:77]
	s_nop 0
	v_pk_fma_f32 v[2:3], v[50:51], v[74:75], v[2:3]
	s_nop 0
	v_add_f32_e32 v99, v2, v3
	ds_write_b128 v91, v[96:99] offset:55296
	s_and_b32 s2, s26, 1
	s_mul_i32 s3, s2, 0x5400
	v_lshlrev_b32_e32 v91, 2, v87
	v_lshl_add_u32 v91, s2, 14, v91
	s_add_i32 s2, s3, 0
	v_add_u32_e32 v0, s2, v85
	v_add_u32_e32 v89, s2, v83
	v_add_u32_e32 v90, s96, v83
	s_add_i32 s96, s96, 0x3000
	s_cmp_eq_u32 s96, 0x1e800
	s_cselect_b32 s96, 0x20200, s96
	s_cmp_eq_u32 s96, 0x23200
	s_cselect_b32 s96, 0x12800, s96
	v_add_u32_e32 v88, s96, v83
	s_cmpk_eq_i32 s26, 0x110
	s_waitcnt lgkmcnt(0)
	s_barrier
	s_cbranch_scc0 .LBB0_1050
	s_setprio 0
